# P1 P3 P10 loops: s_sleep 1 after every 4th ds_read_b128 in the load phase (spread LDS reads under the partner MFMA block)
# speedup vs baseline: 1.0056x; 1.0056x over previous
.LBB0_245:
	ds_read_b128 v[150:153], v147
	ds_read_b128 v[154:157], v147 offset:1024
	ds_read_b128 v[158:161], v147 offset:2048
	ds_read_b128 v[162:165], v147 offset:3072
	s_sleep 1
	ds_read_b128 v[166:169], v148
	ds_read_b128 v[170:173], v148 offset:1024
	ds_read_b128 v[174:177], v148 offset:2048
	ds_read_b128 v[178:181], v148 offset:3072
	s_sleep 1
	s_add_u32 s28, s40, 0xfffc0080
	s_addc_u32 s29, s41, -1
	s_cmp_eq_u32 s77, 12
	s_cselect_b32 s47, s19, s29
	s_cselect_b32 s46, s65, s28
	s_cselect_b32 s43, s15, s76
	s_cselect_b32 s42, s66, s67
	v_lshl_add_u64 v[186:187], s[40:41], 0, v[136:137]
	s_add_i32 m0, s35, 0xc000
	ds_read_b128 v[182:185], v149
	ds_read_b128 v[190:193], v149 offset:1024
	ds_read_b128 v[194:197], v149 offset:2048
	ds_read_b128 v[198:201], v149 offset:3072
	s_sleep 1
	ds_read_b128 v[202:205], v149 offset:4096
	ds_read_b128 v[206:209], v149 offset:5120
	ds_read_b128 v[210:213], v149 offset:6144
	ds_read_b128 v[214:217], v149 offset:7168
	global_load_lds_dwordx4 v[186:187], off
	v_lshl_add_u64 v[186:187], s[40:41], 0, v[138:139]
	s_add_i32 m0, s35, 0xe000
	s_nop 0
	global_load_lds_dwordx4 v[186:187], off
	s_waitcnt vmcnt(8)
	s_waitcnt lgkmcnt(0)
	s_barrier
	s_waitcnt lgkmcnt(0)
	v_mfma_f32_16x16x32_bf16 v[124:127], v[150:153], v[182:185], v[124:127]
	v_mfma_f32_16x16x32_bf16 v[116:119], v[158:161], v[182:185], v[116:119]
	v_mfma_f32_16x16x32_bf16 v[108:111], v[150:153], v[194:197], v[108:111]
	v_mfma_f32_16x16x32_bf16 v[100:103], v[158:161], v[194:197], v[100:103]
	v_mfma_f32_16x16x32_bf16 v[92:95], v[150:153], v[202:205], v[92:95]
	v_mfma_f32_16x16x32_bf16 v[84:87], v[158:161], v[202:205], v[84:87]
	v_mfma_f32_16x16x32_bf16 v[76:79], v[150:153], v[210:213], v[76:79]
	v_mfma_f32_16x16x32_bf16 v[68:71], v[158:161], v[210:213], v[68:71]
	v_mfma_f32_16x16x32_bf16 v[124:127], v[154:157], v[190:193], v[124:127]
	v_mfma_f32_16x16x32_bf16 v[116:119], v[162:165], v[190:193], v[116:119]
	v_mfma_f32_16x16x32_bf16 v[108:111], v[154:157], v[198:201], v[108:111]
	v_mfma_f32_16x16x32_bf16 v[100:103], v[162:165], v[198:201], v[100:103]
	v_mfma_f32_16x16x32_bf16 v[92:95], v[154:157], v[206:209], v[92:95]
	v_mfma_f32_16x16x32_bf16 v[84:87], v[162:165], v[206:209], v[84:87]
	v_mfma_f32_16x16x32_bf16 v[76:79], v[154:157], v[214:217], v[76:79]
	v_mfma_f32_16x16x32_bf16 v[68:71], v[162:165], v[214:217], v[68:71]
	v_mfma_f32_16x16x32_bf16 v[120:123], v[166:169], v[182:185], v[120:123]
	v_mfma_f32_16x16x32_bf16 v[112:115], v[174:177], v[182:185], v[112:115]
	v_mfma_f32_16x16x32_bf16 v[104:107], v[166:169], v[194:197], v[104:107]
	v_mfma_f32_16x16x32_bf16 v[96:99], v[174:177], v[194:197], v[96:99]
	v_mfma_f32_16x16x32_bf16 v[88:91], v[166:169], v[202:205], v[88:91]
	v_mfma_f32_16x16x32_bf16 v[80:83], v[174:177], v[202:205], v[80:83]
	v_mfma_f32_16x16x32_bf16 v[72:75], v[166:169], v[210:213], v[72:75]
	v_mfma_f32_16x16x32_bf16 v[64:67], v[174:177], v[210:213], v[64:67]
	v_mfma_f32_16x16x32_bf16 v[120:123], v[170:173], v[190:193], v[120:123]
	v_mfma_f32_16x16x32_bf16 v[112:115], v[178:181], v[190:193], v[112:115]
	v_mfma_f32_16x16x32_bf16 v[104:107], v[170:173], v[198:201], v[104:107]
	v_mfma_f32_16x16x32_bf16 v[96:99], v[178:181], v[198:201], v[96:99]
	v_mfma_f32_16x16x32_bf16 v[88:91], v[170:173], v[206:209], v[88:91]
	v_mfma_f32_16x16x32_bf16 v[80:83], v[178:181], v[206:209], v[80:83]
	v_mfma_f32_16x16x32_bf16 v[72:75], v[170:173], v[214:217], v[72:75]
	v_mfma_f32_16x16x32_bf16 v[64:67], v[178:181], v[214:217], v[64:67]
	s_barrier
	s_add_i32 s28, s61, s12
	v_lshl_add_u64 v[186:187], s[42:43], 0, v[132:133]
	s_mov_b32 m0, s28
	ds_read_b128 v[182:185], v149 offset:16384
	ds_read_b128 v[190:193], v149 offset:17408
	ds_read_b128 v[194:197], v149 offset:18432
	ds_read_b128 v[198:201], v149 offset:19456
	s_sleep 1
	ds_read_b128 v[202:205], v149 offset:20480
	ds_read_b128 v[206:209], v149 offset:21504
	ds_read_b128 v[210:213], v149 offset:22528
	ds_read_b128 v[214:217], v149 offset:23552
	global_load_lds_dwordx4 v[186:187], off
	s_add_i32 m0, s28, 0x2000
	s_add_u32 s28, s42, 0x40000
	v_lshl_add_u64 v[218:219], s[42:43], 0, v[128:129]
	s_addc_u32 s29, s43, 0
	s_add_i32 s33, s62, s12
	global_load_lds_dwordx4 v[218:219], off
	v_lshl_add_u64 v[220:221], s[28:29], 0, v[132:133]
	s_mov_b32 m0, s33
	v_lshl_add_u64 v[222:223], s[46:47], 0, v[130:131]
	global_load_lds_dwordx4 v[220:221], off
	v_lshl_add_u64 v[220:221], s[28:29], 0, v[128:129]
	s_add_i32 m0, s33, 0x2000
	s_nop 0
	global_load_lds_dwordx4 v[220:221], off
	v_lshl_add_u64 v[220:221], s[46:47], 0, v[134:135]
	s_mov_b32 m0, s35
	s_nop 0
	global_load_lds_dwordx4 v[220:221], off
	s_mov_b32 m0, s39
	s_nop 0
	global_load_lds_dwordx4 v[222:223], off
	s_waitcnt vmcnt(8)
	s_waitcnt lgkmcnt(0)
	s_barrier
	s_waitcnt lgkmcnt(0)
	v_mfma_f32_16x16x32_bf16 v[60:63], v[150:153], v[182:185], v[60:63]
	v_mfma_f32_16x16x32_bf16 v[52:55], v[158:161], v[182:185], v[52:55]
	v_mfma_f32_16x16x32_bf16 v[44:47], v[150:153], v[194:197], v[44:47]
	v_mfma_f32_16x16x32_bf16 v[36:39], v[158:161], v[194:197], v[36:39]
	v_mfma_f32_16x16x32_bf16 v[28:31], v[150:153], v[202:205], v[28:31]
	v_mfma_f32_16x16x32_bf16 v[20:23], v[158:161], v[202:205], v[20:23]
	v_mfma_f32_16x16x32_bf16 v[12:15], v[150:153], v[210:213], v[12:15]
	v_mfma_f32_16x16x32_bf16 v[4:7], v[158:161], v[210:213], v[4:7]
	v_mfma_f32_16x16x32_bf16 v[60:63], v[154:157], v[190:193], v[60:63]
	v_mfma_f32_16x16x32_bf16 v[52:55], v[162:165], v[190:193], v[52:55]
	v_mfma_f32_16x16x32_bf16 v[44:47], v[154:157], v[198:201], v[44:47]
	v_mfma_f32_16x16x32_bf16 v[36:39], v[162:165], v[198:201], v[36:39]
	v_mfma_f32_16x16x32_bf16 v[28:31], v[154:157], v[206:209], v[28:31]
	v_mfma_f32_16x16x32_bf16 v[20:23], v[162:165], v[206:209], v[20:23]
	v_mfma_f32_16x16x32_bf16 v[12:15], v[154:157], v[214:217], v[12:15]
	v_mfma_f32_16x16x32_bf16 v[4:7], v[162:165], v[214:217], v[4:7]
	v_mfma_f32_16x16x32_bf16 v[56:59], v[166:169], v[182:185], v[56:59]
	v_mfma_f32_16x16x32_bf16 v[48:51], v[174:177], v[182:185], v[48:51]
	v_mfma_f32_16x16x32_bf16 v[40:43], v[166:169], v[194:197], v[40:43]
	v_mfma_f32_16x16x32_bf16 v[32:35], v[174:177], v[194:197], v[32:35]
	v_mfma_f32_16x16x32_bf16 v[24:27], v[166:169], v[202:205], v[24:27]
	v_mfma_f32_16x16x32_bf16 v[16:19], v[174:177], v[202:205], v[16:19]
	v_mfma_f32_16x16x32_bf16 v[8:11], v[166:169], v[210:213], v[8:11]
	v_mfma_f32_16x16x32_bf16 v[0:3], v[174:177], v[210:213], v[0:3]
	v_mfma_f32_16x16x32_bf16 v[56:59], v[170:173], v[190:193], v[56:59]
	v_mfma_f32_16x16x32_bf16 v[48:51], v[178:181], v[190:193], v[48:51]
	v_mfma_f32_16x16x32_bf16 v[40:43], v[170:173], v[198:201], v[40:43]
	v_mfma_f32_16x16x32_bf16 v[32:35], v[178:181], v[198:201], v[32:35]
	v_mfma_f32_16x16x32_bf16 v[24:27], v[170:173], v[206:209], v[24:27]
	v_mfma_f32_16x16x32_bf16 v[16:19], v[178:181], v[206:209], v[16:19]
	v_mfma_f32_16x16x32_bf16 v[8:11], v[170:173], v[214:217], v[8:11]
	v_mfma_f32_16x16x32_bf16 v[0:3], v[178:181], v[214:217], v[0:3]
	s_barrier
	s_add_i32 s33, 0, 0x18000
	s_add_i32 s56, 0, 0x1c000
	v_add_u32_e32 v162, s33, v145
	v_add_u32_e32 v178, s56, v145
	ds_read_b128 v[150:153], v162
	ds_read_b128 v[154:157], v162 offset:1024
	ds_read_b128 v[158:161], v162 offset:2048
	ds_read_b128 v[162:165], v162 offset:3072
	s_sleep 1
	ds_read_b128 v[166:169], v178
	ds_read_b128 v[170:173], v178 offset:1024
	ds_read_b128 v[174:177], v178 offset:2048
	ds_read_b128 v[178:181], v178 offset:3072
	s_sleep 1
	s_add_u32 s28, s46, 0x40000
	s_addc_u32 s29, s47, 0
	s_mov_b32 m0, s50
	v_lshl_add_u64 v[224:225], s[28:29], 0, v[134:135]
	ds_read_b128 v[182:185], v149 offset:32768
	ds_read_b128 v[190:193], v149 offset:33792
	ds_read_b128 v[194:197], v149 offset:34816
	ds_read_b128 v[198:201], v149 offset:35840
	s_sleep 1
	ds_read_b128 v[202:205], v149 offset:36864
	ds_read_b128 v[206:209], v149 offset:37888
	ds_read_b128 v[210:213], v149 offset:38912
	ds_read_b128 v[214:217], v149 offset:39936
	global_load_lds_dwordx4 v[224:225], off
	v_lshl_add_u64 v[224:225], s[28:29], 0, v[130:131]
	s_mov_b32 m0, s51
	s_nop 0
	global_load_lds_dwordx4 v[224:225], off
	s_waitcnt vmcnt(8)
	s_waitcnt lgkmcnt(0)
	s_barrier
	s_waitcnt lgkmcnt(0)
	v_mfma_f32_16x16x32_bf16 v[124:127], v[150:153], v[182:185], v[124:127]
	v_mfma_f32_16x16x32_bf16 v[116:119], v[158:161], v[182:185], v[116:119]
	v_mfma_f32_16x16x32_bf16 v[108:111], v[150:153], v[194:197], v[108:111]
	v_mfma_f32_16x16x32_bf16 v[100:103], v[158:161], v[194:197], v[100:103]
	v_mfma_f32_16x16x32_bf16 v[92:95], v[150:153], v[202:205], v[92:95]
	v_mfma_f32_16x16x32_bf16 v[84:87], v[158:161], v[202:205], v[84:87]
	v_mfma_f32_16x16x32_bf16 v[76:79], v[150:153], v[210:213], v[76:79]
	v_mfma_f32_16x16x32_bf16 v[68:71], v[158:161], v[210:213], v[68:71]
	v_mfma_f32_16x16x32_bf16 v[124:127], v[154:157], v[190:193], v[124:127]
	v_mfma_f32_16x16x32_bf16 v[116:119], v[162:165], v[190:193], v[116:119]
	v_mfma_f32_16x16x32_bf16 v[108:111], v[154:157], v[198:201], v[108:111]
	v_mfma_f32_16x16x32_bf16 v[100:103], v[162:165], v[198:201], v[100:103]
	v_mfma_f32_16x16x32_bf16 v[92:95], v[154:157], v[206:209], v[92:95]
	v_mfma_f32_16x16x32_bf16 v[84:87], v[162:165], v[206:209], v[84:87]
	v_mfma_f32_16x16x32_bf16 v[76:79], v[154:157], v[214:217], v[76:79]
	v_mfma_f32_16x16x32_bf16 v[68:71], v[162:165], v[214:217], v[68:71]
	v_mfma_f32_16x16x32_bf16 v[120:123], v[166:169], v[182:185], v[120:123]
	v_mfma_f32_16x16x32_bf16 v[112:115], v[174:177], v[182:185], v[112:115]
	v_mfma_f32_16x16x32_bf16 v[104:107], v[166:169], v[194:197], v[104:107]
	v_mfma_f32_16x16x32_bf16 v[96:99], v[174:177], v[194:197], v[96:99]
	v_mfma_f32_16x16x32_bf16 v[88:91], v[166:169], v[202:205], v[88:91]
	v_mfma_f32_16x16x32_bf16 v[80:83], v[174:177], v[202:205], v[80:83]
	v_mfma_f32_16x16x32_bf16 v[72:75], v[166:169], v[210:213], v[72:75]
	v_mfma_f32_16x16x32_bf16 v[64:67], v[174:177], v[210:213], v[64:67]
	v_mfma_f32_16x16x32_bf16 v[120:123], v[170:173], v[190:193], v[120:123]
	v_mfma_f32_16x16x32_bf16 v[112:115], v[178:181], v[190:193], v[112:115]
	v_mfma_f32_16x16x32_bf16 v[104:107], v[170:173], v[198:201], v[104:107]
	v_mfma_f32_16x16x32_bf16 v[96:99], v[178:181], v[198:201], v[96:99]
	v_mfma_f32_16x16x32_bf16 v[88:91], v[170:173], v[206:209], v[88:91]
	v_mfma_f32_16x16x32_bf16 v[80:83], v[178:181], v[206:209], v[80:83]
	v_mfma_f32_16x16x32_bf16 v[72:75], v[170:173], v[214:217], v[72:75]
	v_mfma_f32_16x16x32_bf16 v[64:67], v[178:181], v[214:217], v[64:67]
	s_barrier
	s_add_i32 s28, s33, s12
	v_lshl_add_u64 v[186:187], v[186:187], 0, s[6:7]
	s_mov_b32 m0, s28
	ds_read_b128 v[182:185], v149 offset:49152
	ds_read_b128 v[190:193], v149 offset:50176
	ds_read_b128 v[194:197], v149 offset:51200
	ds_read_b128 v[198:201], v149 offset:52224
	s_sleep 1
	ds_read_b128 v[202:205], v149 offset:53248
	ds_read_b128 v[206:209], v149 offset:54272
	ds_read_b128 v[210:213], v149 offset:55296
	ds_read_b128 v[214:217], v149 offset:56320
	global_load_lds_dwordx4 v[186:187], off
	s_add_i32 m0, s28, 0x2000
	s_add_u32 s28, s42, 0x40080
	v_lshl_add_u64 v[186:187], v[218:219], 0, s[6:7]
	s_addc_u32 s29, s43, 0
	s_add_i32 s33, s56, s12
	global_load_lds_dwordx4 v[186:187], off
	v_lshl_add_u64 v[186:187], s[28:29], 0, v[132:133]
	s_mov_b32 m0, s33
	s_nop 0
	global_load_lds_dwordx4 v[186:187], off
	v_lshl_add_u64 v[186:187], s[28:29], 0, v[128:129]
	s_add_i32 m0, s33, 0x2000
	s_nop 0
	global_load_lds_dwordx4 v[186:187], off
	v_lshl_add_u64 v[186:187], v[220:221], 0, s[6:7]
	s_mov_b32 m0, s53
	s_nop 0
	global_load_lds_dwordx4 v[186:187], off
	v_lshl_add_u64 v[186:187], v[222:223], 0, s[6:7]
	s_mov_b32 m0, s54
	s_nop 0
	global_load_lds_dwordx4 v[186:187], off
	s_waitcnt vmcnt(8)
	s_waitcnt lgkmcnt(0)
	s_nop 0
	s_barrier
	s_waitcnt lgkmcnt(0)
	v_mfma_f32_16x16x32_bf16 v[60:63], v[150:153], v[182:185], v[60:63]
	v_mfma_f32_16x16x32_bf16 v[52:55], v[158:161], v[182:185], v[52:55]
	v_mfma_f32_16x16x32_bf16 v[44:47], v[150:153], v[194:197], v[44:47]
	v_mfma_f32_16x16x32_bf16 v[36:39], v[158:161], v[194:197], v[36:39]
	v_mfma_f32_16x16x32_bf16 v[28:31], v[150:153], v[202:205], v[28:31]
	v_mfma_f32_16x16x32_bf16 v[20:23], v[158:161], v[202:205], v[20:23]
	v_mfma_f32_16x16x32_bf16 v[12:15], v[150:153], v[210:213], v[12:15]
	v_mfma_f32_16x16x32_bf16 v[4:7], v[158:161], v[210:213], v[4:7]
	v_mfma_f32_16x16x32_bf16 v[60:63], v[154:157], v[190:193], v[60:63]
	v_mfma_f32_16x16x32_bf16 v[52:55], v[162:165], v[190:193], v[52:55]
	v_mfma_f32_16x16x32_bf16 v[44:47], v[154:157], v[198:201], v[44:47]
	v_mfma_f32_16x16x32_bf16 v[36:39], v[162:165], v[198:201], v[36:39]
	v_mfma_f32_16x16x32_bf16 v[28:31], v[154:157], v[206:209], v[28:31]
	v_mfma_f32_16x16x32_bf16 v[20:23], v[162:165], v[206:209], v[20:23]
	v_mfma_f32_16x16x32_bf16 v[12:15], v[154:157], v[214:217], v[12:15]
	v_mfma_f32_16x16x32_bf16 v[4:7], v[162:165], v[214:217], v[4:7]
	v_mfma_f32_16x16x32_bf16 v[56:59], v[166:169], v[182:185], v[56:59]
	v_mfma_f32_16x16x32_bf16 v[48:51], v[174:177], v[182:185], v[48:51]
	v_mfma_f32_16x16x32_bf16 v[40:43], v[166:169], v[194:197], v[40:43]
	v_mfma_f32_16x16x32_bf16 v[32:35], v[174:177], v[194:197], v[32:35]
	v_mfma_f32_16x16x32_bf16 v[24:27], v[166:169], v[202:205], v[24:27]
	v_mfma_f32_16x16x32_bf16 v[16:19], v[174:177], v[202:205], v[16:19]
	v_mfma_f32_16x16x32_bf16 v[8:11], v[166:169], v[210:213], v[8:11]
	v_mfma_f32_16x16x32_bf16 v[0:3], v[174:177], v[210:213], v[0:3]
	v_mfma_f32_16x16x32_bf16 v[56:59], v[170:173], v[190:193], v[56:59]
	v_mfma_f32_16x16x32_bf16 v[48:51], v[178:181], v[190:193], v[48:51]
	v_mfma_f32_16x16x32_bf16 v[40:43], v[170:173], v[198:201], v[40:43]
	v_mfma_f32_16x16x32_bf16 v[32:35], v[178:181], v[198:201], v[32:35]
	v_mfma_f32_16x16x32_bf16 v[24:27], v[170:173], v[206:209], v[24:27]
	v_mfma_f32_16x16x32_bf16 v[16:19], v[178:181], v[206:209], v[16:19]
	v_mfma_f32_16x16x32_bf16 v[8:11], v[170:173], v[214:217], v[8:11]
	v_mfma_f32_16x16x32_bf16 v[0:3], v[178:181], v[214:217], v[0:3]
	s_barrier
	s_add_i32 s77, s77, 2
	s_add_u32 s40, s40, 0x100
	s_addc_u32 s41, s41, 0
	s_add_u32 s67, s67, 0x100
	s_addc_u32 s76, s76, 0
	s_cmp_gt_u32 s77, 13
	s_cbranch_scc0 .LBB0_245
	s_and_b64 vcc, exec, s[8:9]
	s_cbranch_vccz .LBB0_248
	s_barrier

.LBB0_562:
	ds_read_b128 v[40:43], v187
	ds_read_b128 v[44:47], v187 offset:1024
	ds_read_b128 v[56:59], v187 offset:2048
	ds_read_b128 v[60:63], v187 offset:3072
	s_sleep 1
	ds_read_b128 v[168:171], v190
	ds_read_b128 v[172:175], v190 offset:1024
	ds_read_b128 v[192:195], v190 offset:2048
	ds_read_b128 v[196:199], v190 offset:3072
	s_sleep 1
	s_add_u32 s28, s8, 0xfffc0080
	s_addc_u32 s29, s9, -1
	s_cmp_eq_u32 s66, 12
	s_cselect_b32 s63, s7, s29
	s_cselect_b32 s62, s10, s28
	s_cselect_b32 s61, s47, s65
	s_cselect_b32 s60, s51, s64
	v_lshl_add_u64 v[232:233], s[8:9], 0, v[160:161]
	s_add_i32 m0, s82, 0xc000
	ds_read_b128 v[200:203], v191
	ds_read_b128 v[204:207], v191 offset:1024
	ds_read_b128 v[208:211], v191 offset:2048
	ds_read_b128 v[212:215], v191 offset:3072
	s_sleep 1
	ds_read_b128 v[216:219], v191 offset:4096
	ds_read_b128 v[220:223], v191 offset:5120
	ds_read_b128 v[224:227], v191 offset:6144
	ds_read_b128 v[228:231], v191 offset:7168
	global_load_lds_dwordx4 v[232:233], off
	v_lshl_add_u64 v[232:233], s[8:9], 0, v[162:163]
	s_add_i32 m0, s82, 0xe000
	s_nop 0
	global_load_lds_dwordx4 v[232:233], off
	s_waitcnt vmcnt(8)
	s_waitcnt lgkmcnt(0)
	s_nop 0
	s_barrier
	s_waitcnt lgkmcnt(0)
	v_mfma_f32_16x16x32_bf16 v[140:143], v[40:43], v[200:203], v[140:143]
	v_mfma_f32_16x16x32_bf16 v[136:139], v[56:59], v[200:203], v[136:139]
	v_mfma_f32_16x16x32_bf16 v[124:127], v[40:43], v[208:211], v[124:127]
	v_mfma_f32_16x16x32_bf16 v[120:123], v[56:59], v[208:211], v[120:123]
	v_mfma_f32_16x16x32_bf16 v[108:111], v[40:43], v[216:219], v[108:111]
	v_mfma_f32_16x16x32_bf16 v[104:107], v[56:59], v[216:219], v[104:107]
	v_mfma_f32_16x16x32_bf16 v[92:95], v[40:43], v[224:227], v[92:95]
	v_mfma_f32_16x16x32_bf16 v[88:91], v[56:59], v[224:227], v[88:91]
	v_mfma_f32_16x16x32_bf16 v[140:143], v[44:47], v[204:207], v[140:143]
	v_mfma_f32_16x16x32_bf16 v[136:139], v[60:63], v[204:207], v[136:139]
	v_mfma_f32_16x16x32_bf16 v[124:127], v[44:47], v[212:215], v[124:127]
	v_mfma_f32_16x16x32_bf16 v[120:123], v[60:63], v[212:215], v[120:123]
	v_mfma_f32_16x16x32_bf16 v[108:111], v[44:47], v[220:223], v[108:111]
	v_mfma_f32_16x16x32_bf16 v[104:107], v[60:63], v[220:223], v[104:107]
	v_mfma_f32_16x16x32_bf16 v[92:95], v[44:47], v[228:231], v[92:95]
	v_mfma_f32_16x16x32_bf16 v[88:91], v[60:63], v[228:231], v[88:91]
	v_mfma_f32_16x16x32_bf16 v[132:135], v[168:171], v[200:203], v[132:135]
	v_mfma_f32_16x16x32_bf16 v[128:131], v[192:195], v[200:203], v[128:131]
	v_mfma_f32_16x16x32_bf16 v[116:119], v[168:171], v[208:211], v[116:119]
	v_mfma_f32_16x16x32_bf16 v[112:115], v[192:195], v[208:211], v[112:115]
	v_mfma_f32_16x16x32_bf16 v[100:103], v[168:171], v[216:219], v[100:103]
	v_mfma_f32_16x16x32_bf16 v[96:99], v[192:195], v[216:219], v[96:99]
	v_mfma_f32_16x16x32_bf16 v[84:87], v[168:171], v[224:227], v[84:87]
	v_mfma_f32_16x16x32_bf16 v[80:83], v[192:195], v[224:227], v[80:83]
	v_mfma_f32_16x16x32_bf16 v[132:135], v[172:175], v[204:207], v[132:135]
	v_mfma_f32_16x16x32_bf16 v[128:131], v[196:199], v[204:207], v[128:131]
	v_mfma_f32_16x16x32_bf16 v[116:119], v[172:175], v[212:215], v[116:119]
	v_mfma_f32_16x16x32_bf16 v[112:115], v[196:199], v[212:215], v[112:115]
	v_mfma_f32_16x16x32_bf16 v[100:103], v[172:175], v[220:223], v[100:103]
	v_mfma_f32_16x16x32_bf16 v[96:99], v[196:199], v[220:223], v[96:99]
	v_mfma_f32_16x16x32_bf16 v[84:87], v[172:175], v[228:231], v[84:87]
	v_mfma_f32_16x16x32_bf16 v[80:83], v[196:199], v[228:231], v[80:83]
	s_barrier
	s_add_i32 s28, s13, s41
	v_lshl_add_u64 v[232:233], s[60:61], 0, v[146:147]
	s_mov_b32 m0, s28
	ds_read_b128 v[200:203], v191 offset:16384
	ds_read_b128 v[204:207], v191 offset:17408
	ds_read_b128 v[208:211], v191 offset:18432
	ds_read_b128 v[212:215], v191 offset:19456
	s_sleep 1
	ds_read_b128 v[216:219], v191 offset:20480
	ds_read_b128 v[220:223], v191 offset:21504
	ds_read_b128 v[224:227], v191 offset:22528
	ds_read_b128 v[228:231], v191 offset:23552
	global_load_lds_dwordx4 v[232:233], off
	s_add_i32 m0, s28, 0x2000
	s_add_u32 s28, s60, 0x40000
	v_lshl_add_u64 v[234:235], s[60:61], 0, v[150:151]
	s_addc_u32 s29, s61, 0
	s_add_i32 s33, s34, s41
	global_load_lds_dwordx4 v[234:235], off
	v_lshl_add_u64 v[236:237], s[28:29], 0, v[146:147]
	s_mov_b32 m0, s33
	v_lshl_add_u64 v[238:239], s[62:63], 0, v[148:149]
	global_load_lds_dwordx4 v[236:237], off
	v_lshl_add_u64 v[236:237], s[28:29], 0, v[150:151]
	s_add_i32 m0, s33, 0x2000
	s_nop 0
	global_load_lds_dwordx4 v[236:237], off
	v_lshl_add_u64 v[236:237], s[62:63], 0, v[144:145]
	s_mov_b32 m0, s82
	s_nop 0
	global_load_lds_dwordx4 v[236:237], off
	s_mov_b32 m0, s83
	s_nop 0
	global_load_lds_dwordx4 v[238:239], off
	s_waitcnt vmcnt(8)
	s_waitcnt lgkmcnt(0)
	s_barrier
	s_waitcnt lgkmcnt(0)
	v_mfma_f32_16x16x32_bf16 v[76:79], v[40:43], v[200:203], v[76:79]
	v_mfma_f32_16x16x32_bf16 v[72:75], v[56:59], v[200:203], v[72:75]
	v_mfma_f32_16x16x32_bf16 v[52:55], v[40:43], v[208:211], v[52:55]
	v_mfma_f32_16x16x32_bf16 v[48:51], v[56:59], v[208:211], v[48:51]
	v_mfma_f32_16x16x32_bf16 v[28:31], v[40:43], v[216:219], v[28:31]
	v_mfma_f32_16x16x32_bf16 v[24:27], v[56:59], v[216:219], v[24:27]
	v_mfma_f32_16x16x32_bf16 v[12:15], v[40:43], v[224:227], v[12:15]
	v_mfma_f32_16x16x32_bf16 v[8:11], v[56:59], v[224:227], v[8:11]
	v_mfma_f32_16x16x32_bf16 v[76:79], v[44:47], v[204:207], v[76:79]
	v_mfma_f32_16x16x32_bf16 v[72:75], v[60:63], v[204:207], v[72:75]
	v_mfma_f32_16x16x32_bf16 v[52:55], v[44:47], v[212:215], v[52:55]
	v_mfma_f32_16x16x32_bf16 v[48:51], v[60:63], v[212:215], v[48:51]
	v_mfma_f32_16x16x32_bf16 v[28:31], v[44:47], v[220:223], v[28:31]
	v_mfma_f32_16x16x32_bf16 v[24:27], v[60:63], v[220:223], v[24:27]
	v_mfma_f32_16x16x32_bf16 v[12:15], v[44:47], v[228:231], v[12:15]
	v_mfma_f32_16x16x32_bf16 v[8:11], v[60:63], v[228:231], v[8:11]
	v_mfma_f32_16x16x32_bf16 v[36:39], v[168:171], v[208:211], v[36:39]
	v_mfma_f32_16x16x32_bf16 v[32:35], v[192:195], v[208:211], v[32:35]
	v_mfma_f32_16x16x32_bf16 v[20:23], v[168:171], v[216:219], v[20:23]
	v_mfma_f32_16x16x32_bf16 v[16:19], v[192:195], v[216:219], v[16:19]
	v_mfma_f32_16x16x32_bf16 v[4:7], v[168:171], v[224:227], v[4:7]
	v_mfma_f32_16x16x32_bf16 v[0:3], v[192:195], v[224:227], v[0:3]
	v_mfma_f32_16x16x32_bf16 v[40:43], v[168:171], v[200:203], v[68:71]
	v_mfma_f32_16x16x32_bf16 v[44:47], v[192:195], v[200:203], v[64:67]
	v_mfma_f32_16x16x32_bf16 v[36:39], v[172:175], v[212:215], v[36:39]
	v_mfma_f32_16x16x32_bf16 v[32:35], v[196:199], v[212:215], v[32:35]
	v_mfma_f32_16x16x32_bf16 v[20:23], v[172:175], v[220:223], v[20:23]
	v_mfma_f32_16x16x32_bf16 v[16:19], v[196:199], v[220:223], v[16:19]
	v_mfma_f32_16x16x32_bf16 v[4:7], v[172:175], v[228:231], v[4:7]
	v_mfma_f32_16x16x32_bf16 v[0:3], v[196:199], v[228:231], v[0:3]
	v_mfma_f32_16x16x32_bf16 v[40:43], v[172:175], v[204:207], v[40:43]
	v_mfma_f32_16x16x32_bf16 v[44:47], v[196:199], v[204:207], v[44:47]
	s_barrier
	s_add_i32 s33, 0, 0x18000
	s_add_i32 s56, 0, 0x1c000
	v_add_u32_e32 v68, s33, v176
	v_add_u32_e32 v152, s56, v176
	ds_read_b128 v[56:59], v68
	ds_read_b128 v[60:63], v68 offset:1024
	ds_read_b128 v[64:67], v68 offset:2048
	ds_read_b128 v[68:71], v68 offset:3072
	s_sleep 1
	ds_read_b128 v[168:171], v152
	ds_read_b128 v[172:175], v152 offset:1024
	ds_read_b128 v[192:195], v152 offset:2048
	ds_read_b128 v[196:199], v152 offset:3072
	s_sleep 1
	s_add_u32 s28, s62, 0x40000
	s_addc_u32 s29, s63, 0
	s_mov_b32 m0, s92
	v_lshl_add_u64 v[240:241], s[28:29], 0, v[144:145]
	ds_read_b128 v[200:203], v191 offset:32768
	ds_read_b128 v[204:207], v191 offset:33792
	ds_read_b128 v[208:211], v191 offset:34816
	ds_read_b128 v[212:215], v191 offset:35840
	s_sleep 1
	ds_read_b128 v[216:219], v191 offset:36864
	ds_read_b128 v[220:223], v191 offset:37888
	ds_read_b128 v[224:227], v191 offset:38912
	ds_read_b128 v[228:231], v191 offset:39936
	global_load_lds_dwordx4 v[240:241], off
	v_lshl_add_u64 v[240:241], s[28:29], 0, v[148:149]
	s_mov_b32 m0, s93
	s_nop 0
	global_load_lds_dwordx4 v[240:241], off
	s_waitcnt vmcnt(8)
	s_waitcnt lgkmcnt(0)
	s_barrier
	s_waitcnt lgkmcnt(0)
	v_mfma_f32_16x16x32_bf16 v[140:143], v[56:59], v[200:203], v[140:143]
	v_mfma_f32_16x16x32_bf16 v[136:139], v[64:67], v[200:203], v[136:139]
	v_mfma_f32_16x16x32_bf16 v[124:127], v[56:59], v[208:211], v[124:127]
	v_mfma_f32_16x16x32_bf16 v[120:123], v[64:67], v[208:211], v[120:123]
	v_mfma_f32_16x16x32_bf16 v[108:111], v[56:59], v[216:219], v[108:111]
	v_mfma_f32_16x16x32_bf16 v[104:107], v[64:67], v[216:219], v[104:107]
	v_mfma_f32_16x16x32_bf16 v[92:95], v[56:59], v[224:227], v[92:95]
	v_mfma_f32_16x16x32_bf16 v[88:91], v[64:67], v[224:227], v[88:91]
	v_mfma_f32_16x16x32_bf16 v[140:143], v[60:63], v[204:207], v[140:143]
	v_mfma_f32_16x16x32_bf16 v[136:139], v[68:71], v[204:207], v[136:139]
	v_mfma_f32_16x16x32_bf16 v[124:127], v[60:63], v[212:215], v[124:127]
	v_mfma_f32_16x16x32_bf16 v[120:123], v[68:71], v[212:215], v[120:123]
	v_mfma_f32_16x16x32_bf16 v[108:111], v[60:63], v[220:223], v[108:111]
	v_mfma_f32_16x16x32_bf16 v[104:107], v[68:71], v[220:223], v[104:107]
	v_mfma_f32_16x16x32_bf16 v[92:95], v[60:63], v[228:231], v[92:95]
	v_mfma_f32_16x16x32_bf16 v[88:91], v[68:71], v[228:231], v[88:91]
	v_mfma_f32_16x16x32_bf16 v[132:135], v[168:171], v[200:203], v[132:135]
	v_mfma_f32_16x16x32_bf16 v[128:131], v[192:195], v[200:203], v[128:131]
	v_mfma_f32_16x16x32_bf16 v[116:119], v[168:171], v[208:211], v[116:119]
	v_mfma_f32_16x16x32_bf16 v[112:115], v[192:195], v[208:211], v[112:115]
	v_mfma_f32_16x16x32_bf16 v[100:103], v[168:171], v[216:219], v[100:103]
	v_mfma_f32_16x16x32_bf16 v[96:99], v[192:195], v[216:219], v[96:99]
	v_mfma_f32_16x16x32_bf16 v[84:87], v[168:171], v[224:227], v[84:87]
	v_mfma_f32_16x16x32_bf16 v[80:83], v[192:195], v[224:227], v[80:83]
	v_mfma_f32_16x16x32_bf16 v[132:135], v[172:175], v[204:207], v[132:135]
	v_mfma_f32_16x16x32_bf16 v[128:131], v[196:199], v[204:207], v[128:131]
	v_mfma_f32_16x16x32_bf16 v[116:119], v[172:175], v[212:215], v[116:119]
	v_mfma_f32_16x16x32_bf16 v[112:115], v[196:199], v[212:215], v[112:115]
	v_mfma_f32_16x16x32_bf16 v[100:103], v[172:175], v[220:223], v[100:103]
	v_mfma_f32_16x16x32_bf16 v[96:99], v[196:199], v[220:223], v[96:99]
	v_mfma_f32_16x16x32_bf16 v[84:87], v[172:175], v[228:231], v[84:87]
	v_mfma_f32_16x16x32_bf16 v[80:83], v[196:199], v[228:231], v[80:83]
	s_barrier
	s_add_i32 s28, s33, s41
	v_lshl_add_u64 v[232:233], v[232:233], 0, s[16:17]
	s_mov_b32 m0, s28
	ds_read_b128 v[200:203], v191 offset:49152
	ds_read_b128 v[204:207], v191 offset:50176
	ds_read_b128 v[208:211], v191 offset:51200
	ds_read_b128 v[212:215], v191 offset:52224
	s_sleep 1
	ds_read_b128 v[216:219], v191 offset:53248
	ds_read_b128 v[220:223], v191 offset:54272
	ds_read_b128 v[224:227], v191 offset:55296
	ds_read_b128 v[228:231], v191 offset:56320
	global_load_lds_dwordx4 v[232:233], off
	s_add_i32 m0, s28, 0x2000
	s_add_u32 s28, s60, 0x40080
	v_lshl_add_u64 v[232:233], v[234:235], 0, s[16:17]
	s_addc_u32 s29, s61, 0
	s_add_i32 s33, s56, s41
	global_load_lds_dwordx4 v[232:233], off
	v_lshl_add_u64 v[232:233], s[28:29], 0, v[146:147]
	s_mov_b32 m0, s33
	s_nop 0
	global_load_lds_dwordx4 v[232:233], off
	v_lshl_add_u64 v[232:233], s[28:29], 0, v[150:151]
	s_add_i32 m0, s33, 0x2000
	s_nop 0
	global_load_lds_dwordx4 v[232:233], off
	v_lshl_add_u64 v[232:233], v[236:237], 0, s[16:17]
	s_mov_b32 m0, s3
	s_nop 0
	global_load_lds_dwordx4 v[232:233], off
	v_lshl_add_u64 v[232:233], v[238:239], 0, s[16:17]
	s_mov_b32 m0, s78
	s_nop 0
	global_load_lds_dwordx4 v[232:233], off
	s_waitcnt vmcnt(8)
	s_waitcnt lgkmcnt(0)
	s_nop 0
	s_barrier
	s_waitcnt lgkmcnt(0)
	v_mfma_f32_16x16x32_bf16 v[76:79], v[56:59], v[200:203], v[76:79]
	v_mfma_f32_16x16x32_bf16 v[72:75], v[64:67], v[200:203], v[72:75]
	v_mfma_f32_16x16x32_bf16 v[52:55], v[56:59], v[208:211], v[52:55]
	v_mfma_f32_16x16x32_bf16 v[48:51], v[64:67], v[208:211], v[48:51]
	v_mfma_f32_16x16x32_bf16 v[28:31], v[56:59], v[216:219], v[28:31]
	v_mfma_f32_16x16x32_bf16 v[24:27], v[64:67], v[216:219], v[24:27]
	v_mfma_f32_16x16x32_bf16 v[12:15], v[56:59], v[224:227], v[12:15]
	v_mfma_f32_16x16x32_bf16 v[8:11], v[64:67], v[224:227], v[8:11]
	v_mfma_f32_16x16x32_bf16 v[76:79], v[60:63], v[204:207], v[76:79]
	v_mfma_f32_16x16x32_bf16 v[72:75], v[68:71], v[204:207], v[72:75]
	v_mfma_f32_16x16x32_bf16 v[52:55], v[60:63], v[212:215], v[52:55]
	v_mfma_f32_16x16x32_bf16 v[48:51], v[68:71], v[212:215], v[48:51]
	v_mfma_f32_16x16x32_bf16 v[28:31], v[60:63], v[220:223], v[28:31]
	v_mfma_f32_16x16x32_bf16 v[24:27], v[68:71], v[220:223], v[24:27]
	v_mfma_f32_16x16x32_bf16 v[12:15], v[60:63], v[228:231], v[12:15]
	v_mfma_f32_16x16x32_bf16 v[8:11], v[68:71], v[228:231], v[8:11]
	v_mfma_f32_16x16x32_bf16 v[40:43], v[168:171], v[200:203], v[40:43]
	v_mfma_f32_16x16x32_bf16 v[68:71], v[172:175], v[204:207], v[40:43]
	v_mfma_f32_16x16x32_bf16 v[40:43], v[192:195], v[200:203], v[44:47]
	v_mfma_f32_16x16x32_bf16 v[36:39], v[168:171], v[208:211], v[36:39]
	v_mfma_f32_16x16x32_bf16 v[32:35], v[192:195], v[208:211], v[32:35]
	v_mfma_f32_16x16x32_bf16 v[20:23], v[168:171], v[216:219], v[20:23]
	v_mfma_f32_16x16x32_bf16 v[16:19], v[192:195], v[216:219], v[16:19]
	v_mfma_f32_16x16x32_bf16 v[4:7], v[168:171], v[224:227], v[4:7]
	v_mfma_f32_16x16x32_bf16 v[0:3], v[192:195], v[224:227], v[0:3]
	v_mfma_f32_16x16x32_bf16 v[64:67], v[196:199], v[204:207], v[40:43]
	v_mfma_f32_16x16x32_bf16 v[36:39], v[172:175], v[212:215], v[36:39]
	v_mfma_f32_16x16x32_bf16 v[32:35], v[196:199], v[212:215], v[32:35]
	v_mfma_f32_16x16x32_bf16 v[20:23], v[172:175], v[220:223], v[20:23]
	v_mfma_f32_16x16x32_bf16 v[16:19], v[196:199], v[220:223], v[16:19]
	v_mfma_f32_16x16x32_bf16 v[4:7], v[172:175], v[228:231], v[4:7]
	v_mfma_f32_16x16x32_bf16 v[0:3], v[196:199], v[228:231], v[0:3]
	s_barrier
	s_add_i32 s66, s66, 2
	s_add_u32 s8, s8, 0x100
	s_addc_u32 s9, s9, 0
	s_add_u32 s64, s64, 0x100
	s_addc_u32 s65, s65, 0
	s_cmp_gt_u32 s66, 13
	s_cbranch_scc0 .LBB0_562
	s_and_b64 vcc, exec, s[18:19]
	s_cbranch_vccz .LBB0_565
	s_barrier

.LBB0_1308:
	ds_read_b128 v[150:153], v147
	ds_read_b128 v[154:157], v147 offset:1024
	ds_read_b128 v[158:161], v147 offset:2048
	ds_read_b128 v[162:165], v147 offset:3072
	s_sleep 1
	ds_read_b128 v[166:169], v148
	ds_read_b128 v[170:173], v148 offset:1024
	ds_read_b128 v[174:177], v148 offset:2048
	ds_read_b128 v[178:181], v148 offset:3072
	s_sleep 1
	s_add_u32 s33, s38, 0xfffc0080
	s_addc_u32 s40, s39, -1
	s_cmp_eq_u32 s56, 12
	s_cselect_b32 s43, s19, s40
	s_cselect_b32 s42, s52, s33
	s_cselect_b32 s41, s17, s55
	s_cselect_b32 s40, s53, s54
	v_lshl_add_u64 v[186:187], s[38:39], 0, v[136:137]
	s_add_i32 m0, s34, 0xc000
	ds_read_b128 v[182:185], v149
	ds_read_b128 v[190:193], v149 offset:1024
	ds_read_b128 v[194:197], v149 offset:2048
	ds_read_b128 v[198:201], v149 offset:3072
	s_sleep 1
	ds_read_b128 v[202:205], v149 offset:4096
	ds_read_b128 v[206:209], v149 offset:5120
	ds_read_b128 v[210:213], v149 offset:6144
	ds_read_b128 v[214:217], v149 offset:7168
	global_load_lds_dwordx4 v[186:187], off
	v_lshl_add_u64 v[186:187], s[38:39], 0, v[138:139]
	s_add_i32 m0, s34, 0xe000
	s_nop 0
	global_load_lds_dwordx4 v[186:187], off
	s_waitcnt vmcnt(8)
	s_waitcnt lgkmcnt(0)
	s_barrier
	s_waitcnt lgkmcnt(0)
	v_mfma_f32_16x16x32_bf16 v[124:127], v[150:153], v[182:185], v[124:127]
	v_mfma_f32_16x16x32_bf16 v[116:119], v[158:161], v[182:185], v[116:119]
	v_mfma_f32_16x16x32_bf16 v[108:111], v[150:153], v[194:197], v[108:111]
	v_mfma_f32_16x16x32_bf16 v[100:103], v[158:161], v[194:197], v[100:103]
	v_mfma_f32_16x16x32_bf16 v[92:95], v[150:153], v[202:205], v[92:95]
	v_mfma_f32_16x16x32_bf16 v[84:87], v[158:161], v[202:205], v[84:87]
	v_mfma_f32_16x16x32_bf16 v[76:79], v[150:153], v[210:213], v[76:79]
	v_mfma_f32_16x16x32_bf16 v[68:71], v[158:161], v[210:213], v[68:71]
	v_mfma_f32_16x16x32_bf16 v[124:127], v[154:157], v[190:193], v[124:127]
	v_mfma_f32_16x16x32_bf16 v[116:119], v[162:165], v[190:193], v[116:119]
	v_mfma_f32_16x16x32_bf16 v[108:111], v[154:157], v[198:201], v[108:111]
	v_mfma_f32_16x16x32_bf16 v[100:103], v[162:165], v[198:201], v[100:103]
	v_mfma_f32_16x16x32_bf16 v[92:95], v[154:157], v[206:209], v[92:95]
	v_mfma_f32_16x16x32_bf16 v[84:87], v[162:165], v[206:209], v[84:87]
	v_mfma_f32_16x16x32_bf16 v[76:79], v[154:157], v[214:217], v[76:79]
	v_mfma_f32_16x16x32_bf16 v[68:71], v[162:165], v[214:217], v[68:71]
	v_mfma_f32_16x16x32_bf16 v[120:123], v[166:169], v[182:185], v[120:123]
	v_mfma_f32_16x16x32_bf16 v[112:115], v[174:177], v[182:185], v[112:115]
	v_mfma_f32_16x16x32_bf16 v[104:107], v[166:169], v[194:197], v[104:107]
	v_mfma_f32_16x16x32_bf16 v[96:99], v[174:177], v[194:197], v[96:99]
	v_mfma_f32_16x16x32_bf16 v[88:91], v[166:169], v[202:205], v[88:91]
	v_mfma_f32_16x16x32_bf16 v[80:83], v[174:177], v[202:205], v[80:83]
	v_mfma_f32_16x16x32_bf16 v[72:75], v[166:169], v[210:213], v[72:75]
	v_mfma_f32_16x16x32_bf16 v[64:67], v[174:177], v[210:213], v[64:67]
	v_mfma_f32_16x16x32_bf16 v[120:123], v[170:173], v[190:193], v[120:123]
	v_mfma_f32_16x16x32_bf16 v[112:115], v[178:181], v[190:193], v[112:115]
	v_mfma_f32_16x16x32_bf16 v[104:107], v[170:173], v[198:201], v[104:107]
	v_mfma_f32_16x16x32_bf16 v[96:99], v[178:181], v[198:201], v[96:99]
	v_mfma_f32_16x16x32_bf16 v[88:91], v[170:173], v[206:209], v[88:91]
	v_mfma_f32_16x16x32_bf16 v[80:83], v[178:181], v[206:209], v[80:83]
	v_mfma_f32_16x16x32_bf16 v[72:75], v[170:173], v[214:217], v[72:75]
	v_mfma_f32_16x16x32_bf16 v[64:67], v[178:181], v[214:217], v[64:67]
	s_barrier
	s_add_i32 s33, s48, s13
	v_lshl_add_u64 v[186:187], s[40:41], 0, v[132:133]
	s_mov_b32 m0, s33
	ds_read_b128 v[182:185], v149 offset:16384
	ds_read_b128 v[190:193], v149 offset:17408
	ds_read_b128 v[194:197], v149 offset:18432
	ds_read_b128 v[198:201], v149 offset:19456
	s_sleep 1
	ds_read_b128 v[202:205], v149 offset:20480
	ds_read_b128 v[206:209], v149 offset:21504
	ds_read_b128 v[210:213], v149 offset:22528
	ds_read_b128 v[214:217], v149 offset:23552
	global_load_lds_dwordx4 v[186:187], off
	s_add_i32 m0, s33, 0x2000
	s_add_u32 s58, s40, 0x40000
	v_lshl_add_u64 v[218:219], s[40:41], 0, v[128:129]
	s_addc_u32 s59, s41, 0
	s_add_i32 s33, s49, s13
	global_load_lds_dwordx4 v[218:219], off
	v_lshl_add_u64 v[220:221], s[58:59], 0, v[132:133]
	s_mov_b32 m0, s33
	v_lshl_add_u64 v[222:223], s[42:43], 0, v[130:131]
	global_load_lds_dwordx4 v[220:221], off
	v_lshl_add_u64 v[220:221], s[58:59], 0, v[128:129]
	s_add_i32 m0, s33, 0x2000
	s_nop 0
	global_load_lds_dwordx4 v[220:221], off
	v_lshl_add_u64 v[220:221], s[42:43], 0, v[134:135]
	s_mov_b32 m0, s34
	s_nop 0
	global_load_lds_dwordx4 v[220:221], off
	s_mov_b32 m0, s35
	s_nop 0
	global_load_lds_dwordx4 v[222:223], off
	s_waitcnt vmcnt(8)
	s_waitcnt lgkmcnt(0)
	s_barrier
	s_waitcnt lgkmcnt(0)
	v_mfma_f32_16x16x32_bf16 v[60:63], v[150:153], v[182:185], v[60:63]
	v_mfma_f32_16x16x32_bf16 v[52:55], v[158:161], v[182:185], v[52:55]
	v_mfma_f32_16x16x32_bf16 v[44:47], v[150:153], v[194:197], v[44:47]
	v_mfma_f32_16x16x32_bf16 v[36:39], v[158:161], v[194:197], v[36:39]
	v_mfma_f32_16x16x32_bf16 v[28:31], v[150:153], v[202:205], v[28:31]
	v_mfma_f32_16x16x32_bf16 v[20:23], v[158:161], v[202:205], v[20:23]
	v_mfma_f32_16x16x32_bf16 v[12:15], v[150:153], v[210:213], v[12:15]
	v_mfma_f32_16x16x32_bf16 v[4:7], v[158:161], v[210:213], v[4:7]
	v_mfma_f32_16x16x32_bf16 v[60:63], v[154:157], v[190:193], v[60:63]
	v_mfma_f32_16x16x32_bf16 v[52:55], v[162:165], v[190:193], v[52:55]
	v_mfma_f32_16x16x32_bf16 v[44:47], v[154:157], v[198:201], v[44:47]
	v_mfma_f32_16x16x32_bf16 v[36:39], v[162:165], v[198:201], v[36:39]
	v_mfma_f32_16x16x32_bf16 v[28:31], v[154:157], v[206:209], v[28:31]
	v_mfma_f32_16x16x32_bf16 v[20:23], v[162:165], v[206:209], v[20:23]
	v_mfma_f32_16x16x32_bf16 v[12:15], v[154:157], v[214:217], v[12:15]
	v_mfma_f32_16x16x32_bf16 v[4:7], v[162:165], v[214:217], v[4:7]
	v_mfma_f32_16x16x32_bf16 v[56:59], v[166:169], v[182:185], v[56:59]
	v_mfma_f32_16x16x32_bf16 v[48:51], v[174:177], v[182:185], v[48:51]
	v_mfma_f32_16x16x32_bf16 v[40:43], v[166:169], v[194:197], v[40:43]
	v_mfma_f32_16x16x32_bf16 v[32:35], v[174:177], v[194:197], v[32:35]
	v_mfma_f32_16x16x32_bf16 v[24:27], v[166:169], v[202:205], v[24:27]
	v_mfma_f32_16x16x32_bf16 v[16:19], v[174:177], v[202:205], v[16:19]
	v_mfma_f32_16x16x32_bf16 v[8:11], v[166:169], v[210:213], v[8:11]
	v_mfma_f32_16x16x32_bf16 v[0:3], v[174:177], v[210:213], v[0:3]
	v_mfma_f32_16x16x32_bf16 v[56:59], v[170:173], v[190:193], v[56:59]
	v_mfma_f32_16x16x32_bf16 v[48:51], v[178:181], v[190:193], v[48:51]
	v_mfma_f32_16x16x32_bf16 v[40:43], v[170:173], v[198:201], v[40:43]
	v_mfma_f32_16x16x32_bf16 v[32:35], v[178:181], v[198:201], v[32:35]
	v_mfma_f32_16x16x32_bf16 v[24:27], v[170:173], v[206:209], v[24:27]
	v_mfma_f32_16x16x32_bf16 v[16:19], v[178:181], v[206:209], v[16:19]
	v_mfma_f32_16x16x32_bf16 v[8:11], v[170:173], v[214:217], v[8:11]
	v_mfma_f32_16x16x32_bf16 v[0:3], v[178:181], v[214:217], v[0:3]
	s_barrier
	s_add_i32 s33, 0, 0x18000
	s_add_i32 s57, 0, 0x1c000
	v_add_u32_e32 v162, s33, v145
	v_add_u32_e32 v178, s57, v145
	ds_read_b128 v[150:153], v162
	ds_read_b128 v[154:157], v162 offset:1024
	ds_read_b128 v[158:161], v162 offset:2048
	ds_read_b128 v[162:165], v162 offset:3072
	s_sleep 1
	ds_read_b128 v[166:169], v178
	ds_read_b128 v[170:173], v178 offset:1024
	ds_read_b128 v[174:177], v178 offset:2048
	ds_read_b128 v[178:181], v178 offset:3072
	s_sleep 1
	s_add_u32 s42, s42, 0x40000
	s_addc_u32 s43, s43, 0
	s_mov_b32 m0, s37
	v_lshl_add_u64 v[224:225], s[42:43], 0, v[134:135]
	ds_read_b128 v[182:185], v149 offset:32768
	ds_read_b128 v[190:193], v149 offset:33792
	ds_read_b128 v[194:197], v149 offset:34816
	ds_read_b128 v[198:201], v149 offset:35840
	s_sleep 1
	ds_read_b128 v[202:205], v149 offset:36864
	ds_read_b128 v[206:209], v149 offset:37888
	ds_read_b128 v[210:213], v149 offset:38912
	ds_read_b128 v[214:217], v149 offset:39936
	global_load_lds_dwordx4 v[224:225], off
	v_lshl_add_u64 v[224:225], s[42:43], 0, v[130:131]
	s_mov_b32 m0, s44
	s_nop 0
	global_load_lds_dwordx4 v[224:225], off
	s_waitcnt vmcnt(8)
	s_waitcnt lgkmcnt(0)
	s_barrier
	s_waitcnt lgkmcnt(0)
	v_mfma_f32_16x16x32_bf16 v[124:127], v[150:153], v[182:185], v[124:127]
	v_mfma_f32_16x16x32_bf16 v[116:119], v[158:161], v[182:185], v[116:119]
	v_mfma_f32_16x16x32_bf16 v[108:111], v[150:153], v[194:197], v[108:111]
	v_mfma_f32_16x16x32_bf16 v[100:103], v[158:161], v[194:197], v[100:103]
	v_mfma_f32_16x16x32_bf16 v[92:95], v[150:153], v[202:205], v[92:95]
	v_mfma_f32_16x16x32_bf16 v[84:87], v[158:161], v[202:205], v[84:87]
	v_mfma_f32_16x16x32_bf16 v[76:79], v[150:153], v[210:213], v[76:79]
	v_mfma_f32_16x16x32_bf16 v[68:71], v[158:161], v[210:213], v[68:71]
	v_mfma_f32_16x16x32_bf16 v[124:127], v[154:157], v[190:193], v[124:127]
	v_mfma_f32_16x16x32_bf16 v[116:119], v[162:165], v[190:193], v[116:119]
	v_mfma_f32_16x16x32_bf16 v[108:111], v[154:157], v[198:201], v[108:111]
	v_mfma_f32_16x16x32_bf16 v[100:103], v[162:165], v[198:201], v[100:103]
	v_mfma_f32_16x16x32_bf16 v[92:95], v[154:157], v[206:209], v[92:95]
	v_mfma_f32_16x16x32_bf16 v[84:87], v[162:165], v[206:209], v[84:87]
	v_mfma_f32_16x16x32_bf16 v[76:79], v[154:157], v[214:217], v[76:79]
	v_mfma_f32_16x16x32_bf16 v[68:71], v[162:165], v[214:217], v[68:71]
	v_mfma_f32_16x16x32_bf16 v[120:123], v[166:169], v[182:185], v[120:123]
	v_mfma_f32_16x16x32_bf16 v[112:115], v[174:177], v[182:185], v[112:115]
	v_mfma_f32_16x16x32_bf16 v[104:107], v[166:169], v[194:197], v[104:107]
	v_mfma_f32_16x16x32_bf16 v[96:99], v[174:177], v[194:197], v[96:99]
	v_mfma_f32_16x16x32_bf16 v[88:91], v[166:169], v[202:205], v[88:91]
	v_mfma_f32_16x16x32_bf16 v[80:83], v[174:177], v[202:205], v[80:83]
	v_mfma_f32_16x16x32_bf16 v[72:75], v[166:169], v[210:213], v[72:75]
	v_mfma_f32_16x16x32_bf16 v[64:67], v[174:177], v[210:213], v[64:67]
	v_mfma_f32_16x16x32_bf16 v[120:123], v[170:173], v[190:193], v[120:123]
	v_mfma_f32_16x16x32_bf16 v[112:115], v[178:181], v[190:193], v[112:115]
	v_mfma_f32_16x16x32_bf16 v[104:107], v[170:173], v[198:201], v[104:107]
	v_mfma_f32_16x16x32_bf16 v[96:99], v[178:181], v[198:201], v[96:99]
	v_mfma_f32_16x16x32_bf16 v[88:91], v[170:173], v[206:209], v[88:91]
	v_mfma_f32_16x16x32_bf16 v[80:83], v[178:181], v[206:209], v[80:83]
	v_mfma_f32_16x16x32_bf16 v[72:75], v[170:173], v[214:217], v[72:75]
	v_mfma_f32_16x16x32_bf16 v[64:67], v[178:181], v[214:217], v[64:67]
	s_barrier
	s_add_i32 s33, s33, s13
	v_lshl_add_u64 v[186:187], v[186:187], 0, s[8:9]
	s_mov_b32 m0, s33
	ds_read_b128 v[182:185], v149 offset:49152
	ds_read_b128 v[190:193], v149 offset:50176
	ds_read_b128 v[194:197], v149 offset:51200
	ds_read_b128 v[198:201], v149 offset:52224
	s_sleep 1
	ds_read_b128 v[202:205], v149 offset:53248
	ds_read_b128 v[206:209], v149 offset:54272
	ds_read_b128 v[210:213], v149 offset:55296
	ds_read_b128 v[214:217], v149 offset:56320
	global_load_lds_dwordx4 v[186:187], off
	s_add_i32 m0, s33, 0x2000
	s_add_u32 s40, s40, 0x40080
	v_lshl_add_u64 v[186:187], v[218:219], 0, s[8:9]
	s_addc_u32 s41, s41, 0
	s_add_i32 s33, s57, s13
	global_load_lds_dwordx4 v[186:187], off
	v_lshl_add_u64 v[186:187], s[40:41], 0, v[132:133]
	s_mov_b32 m0, s33
	s_nop 0
	global_load_lds_dwordx4 v[186:187], off
	v_lshl_add_u64 v[186:187], s[40:41], 0, v[128:129]
	s_add_i32 m0, s33, 0x2000
	s_nop 0
	global_load_lds_dwordx4 v[186:187], off
	v_lshl_add_u64 v[186:187], v[220:221], 0, s[8:9]
	s_mov_b32 m0, s46
	s_nop 0
	global_load_lds_dwordx4 v[186:187], off
	v_lshl_add_u64 v[186:187], v[222:223], 0, s[8:9]
	s_mov_b32 m0, s47
	s_nop 0
	global_load_lds_dwordx4 v[186:187], off
	s_waitcnt vmcnt(8)
	s_waitcnt lgkmcnt(0)
	s_nop 0
	s_barrier
	s_waitcnt lgkmcnt(0)
	v_mfma_f32_16x16x32_bf16 v[60:63], v[150:153], v[182:185], v[60:63]
	v_mfma_f32_16x16x32_bf16 v[52:55], v[158:161], v[182:185], v[52:55]
	v_mfma_f32_16x16x32_bf16 v[44:47], v[150:153], v[194:197], v[44:47]
	v_mfma_f32_16x16x32_bf16 v[36:39], v[158:161], v[194:197], v[36:39]
	v_mfma_f32_16x16x32_bf16 v[28:31], v[150:153], v[202:205], v[28:31]
	v_mfma_f32_16x16x32_bf16 v[20:23], v[158:161], v[202:205], v[20:23]
	v_mfma_f32_16x16x32_bf16 v[12:15], v[150:153], v[210:213], v[12:15]
	v_mfma_f32_16x16x32_bf16 v[4:7], v[158:161], v[210:213], v[4:7]
	v_mfma_f32_16x16x32_bf16 v[60:63], v[154:157], v[190:193], v[60:63]
	v_mfma_f32_16x16x32_bf16 v[52:55], v[162:165], v[190:193], v[52:55]
	v_mfma_f32_16x16x32_bf16 v[44:47], v[154:157], v[198:201], v[44:47]
	v_mfma_f32_16x16x32_bf16 v[36:39], v[162:165], v[198:201], v[36:39]
	v_mfma_f32_16x16x32_bf16 v[28:31], v[154:157], v[206:209], v[28:31]
	v_mfma_f32_16x16x32_bf16 v[20:23], v[162:165], v[206:209], v[20:23]
	v_mfma_f32_16x16x32_bf16 v[12:15], v[154:157], v[214:217], v[12:15]
	v_mfma_f32_16x16x32_bf16 v[4:7], v[162:165], v[214:217], v[4:7]
	v_mfma_f32_16x16x32_bf16 v[56:59], v[166:169], v[182:185], v[56:59]
	v_mfma_f32_16x16x32_bf16 v[48:51], v[174:177], v[182:185], v[48:51]
	v_mfma_f32_16x16x32_bf16 v[40:43], v[166:169], v[194:197], v[40:43]
	v_mfma_f32_16x16x32_bf16 v[32:35], v[174:177], v[194:197], v[32:35]
	v_mfma_f32_16x16x32_bf16 v[24:27], v[166:169], v[202:205], v[24:27]
	v_mfma_f32_16x16x32_bf16 v[16:19], v[174:177], v[202:205], v[16:19]
	v_mfma_f32_16x16x32_bf16 v[8:11], v[166:169], v[210:213], v[8:11]
	v_mfma_f32_16x16x32_bf16 v[0:3], v[174:177], v[210:213], v[0:3]
	v_mfma_f32_16x16x32_bf16 v[56:59], v[170:173], v[190:193], v[56:59]
	v_mfma_f32_16x16x32_bf16 v[48:51], v[178:181], v[190:193], v[48:51]
	v_mfma_f32_16x16x32_bf16 v[40:43], v[170:173], v[198:201], v[40:43]
	v_mfma_f32_16x16x32_bf16 v[32:35], v[178:181], v[198:201], v[32:35]
	v_mfma_f32_16x16x32_bf16 v[24:27], v[170:173], v[206:209], v[24:27]
	v_mfma_f32_16x16x32_bf16 v[16:19], v[178:181], v[206:209], v[16:19]
	v_mfma_f32_16x16x32_bf16 v[8:11], v[170:173], v[214:217], v[8:11]
	v_mfma_f32_16x16x32_bf16 v[0:3], v[178:181], v[214:217], v[0:3]
	s_barrier
	s_add_i32 s56, s56, 2
	s_add_u32 s38, s38, 0x100
	s_addc_u32 s39, s39, 0
	s_add_u32 s54, s54, 0x100
	s_addc_u32 s55, s55, 0
	s_cmp_gt_u32 s56, 13
	s_cbranch_scc0 .LBB0_1308
	s_and_b64 vcc, exec, s[10:11]
	s_cbranch_vccz .LBB0_1311
	s_barrier
